# attention PV regions: lgkmcnt(0) drains replaced by counted waits per MFMA (transposed V reads stay in flight)
# speedup vs baseline: 1.0184x; 1.0072x over previous
; __device__ __forceinline__ void finishSM(f32x16& p0, f32x16& p1, float alpha, float& l_reg, bf16x8& pa0, bf16x8& pa1, bf16x8& pa2, bf16x8& pa3) {
; #pragma unroll
;     for (int r = 0; r < 16; ++r) p1[r] = __builtin_amdgcn_exp2f(p1[r]);
;     float ps = 0;
; #pragma unroll
;     for (int r = 0; r < 16; ++r) ps += p0[r];
; #pragma unroll
;     for (int r = 0; r < 16; ++r) ps += p1[r];
;     { auto rr = __builtin_amdgcn_permlane32_swap(__float_as_uint(ps), __float_as_uint(ps), false, false);
;       ps = __uint_as_float(rr[0]) + __uint_as_float(rr[1]); }
;     l_reg = l_reg * alpha + ps;
;     ...
;     PK4(p0, 0, pa0); PK4(p0, 8, pa1); PK4(p1, 0, pa2); PK4(p1, 8, pa3);
;     ...
; }
; template <int KB>
; __device__ __forceinline__ void qkt(f32x16& p0, f32x16& p1, const char* K_lds, int r32, int hi, const bf16x8* qr) {
;     p0 = f32x16{}; p1 = f32x16{};
;     const char* kb[4];
; #pragma unroll
;     for (int dd = 0; dd < 4; ++dd) kb[dd] = K_lds + KB * SHM_K + KSWZ(r32, (dd * 16 + hi * 8) * 2);
; #pragma unroll
;     for (int d0 = 0; d0 < 8; ++d0) { const char* a = kb[d0 & 3] + (d0 >> 2) * 128;
;         bf16x8 b0 = *reinterpret_cast<const bf16x8*>(a);
;         bf16x8 b1 = *reinterpret_cast<const bf16x8*>(a + 32 * 256);
;         p0 = __builtin_amdgcn_mfma_f32_32x32x16_bf16(b0, qr[d0], p0, 0, 0, 0);
;         p1 = __builtin_amdgcn_mfma_f32_32x32x16_bf16(b1, qr[d0], p1, 0, 0, 0); }
; }
; template <int VB>
; __device__ __forceinline__ void pv_tile(f32x16* o, int vb0, bf16x8 pa0, bf16x8 pa1, bf16x8 pa2, bf16x8 pa3) {
;     ...
;     PV_D0(0); PV_D0(1); PV_D0(2); PV_D0(3);
.LBB0_1299:
	v_add_u32_e32 v146, -8, v179
	global_load_dwordx2 v[146:147], v146, s[68:69]
	v_lshl_add_u64 v[130:131], v[188:189], 0, v[170:171]
	v_lshl_add_u64 v[138:139], v[190:191], 0, v[170:171]
	v_lshl_add_u64 v[134:135], v[130:131], 0, s[100:101]
	v_lshl_add_u64 v[130:131], v[130:131], 0, s[16:17]
	v_lshl_add_u64 v[142:143], v[138:139], 0, s[100:101]
	v_lshl_add_u64 v[138:139], v[138:139], 0, s[16:17]
	global_load_dwordx4 v[130:133], v[130:131], off
	global_load_dwordx4 v[134:137], v[134:135], off
	global_load_dwordx4 v[138:141], v[138:139], off
	global_load_dwordx4 v[142:145], v[142:143], off
	ds_read_b128 v[66:69], v199 offset:49152
	ds_read_b128 v[82:85], v199 offset:57344
	ds_read_b128 v[172:175], v200 offset:49152
	ds_read_b128 v[232:235], v200 offset:57344
	ds_read_b128 v[236:239], v201 offset:49152
	ds_read_b128 v[240:243], v201 offset:57344
	ds_read_b128 v[244:247], v202 offset:49152
	v_exp_f32_e32 v209, v150
	v_add_f32_e32 v150, 0, v219
	v_add_f32_e32 v150, v220, v150
	v_add_f32_e32 v150, v221, v150
	s_waitcnt lgkmcnt(6)
	v_mfma_f32_32x32x16_bf16 v[66:81], v[66:69], v[126:129], 0
	v_add_f32_e32 v150, v222, v150
	v_add_f32_e32 v150, v223, v150
	v_add_f32_e32 v150, v225, v150
	v_add_f32_e32 v150, v224, v150
	v_add_f32_e32 v150, v226, v150
	s_waitcnt lgkmcnt(5)
	v_mfma_f32_32x32x16_bf16 v[82:97], v[82:85], v[126:129], 0
	v_add_f32_e32 v150, v211, v150
	v_add_f32_e32 v150, v212, v150
	v_exp_f32_e32 v194, v194
	s_waitcnt lgkmcnt(4)
	v_mfma_f32_32x32x16_bf16 v[66:81], v[172:175], v[122:125], v[66:81]
	ds_read_b128 v[172:175], v202 offset:57344
	v_exp_f32_e32 v195, v195
	v_exp_f32_e32 v192, v192
	v_exp_f32_e32 v193, v193
	s_waitcnt lgkmcnt(4)
	v_mfma_f32_32x32x16_bf16 v[82:97], v[232:235], v[122:125], v[82:97]
	ds_read_b128 v[232:235], v199 offset:49280
	v_exp_f32_e32 v158, v158
	v_exp_f32_e32 v159, v159
	s_waitcnt lgkmcnt(4)
	v_mfma_f32_32x32x16_bf16 v[66:81], v[236:239], v[118:121], v[66:81]
	ds_read_b128 v[236:239], v199 offset:57472
	v_exp_f32_e32 v207, v154
	v_exp_f32_e32 v208, v155
	v_exp_f32_e32 v210, v151
	s_waitcnt lgkmcnt(4)
	v_mfma_f32_32x32x16_bf16 v[82:97], v[240:243], v[118:121], v[82:97]
	ds_read_b128 v[240:243], v200 offset:49280
	v_exp_f32_e32 v160, v160
	v_exp_f32_e32 v161, v161
	s_waitcnt lgkmcnt(4)
	v_mfma_f32_32x32x16_bf16 v[66:81], v[244:247], v[114:117], v[66:81]
	ds_read_b128 v[244:247], v200 offset:57472
	v_exp_f32_e32 v227, v156
	v_cvt_pk_bf16_f32 v151, v224, v226
	v_cvt_pk_bf16_f32 v154, v214, v216
	v_cvt_pk_bf16_f32 v155, v217, v218
	v_cvt_pk_bf16_f32 v156, v194, v195
	s_waitcnt lgkmcnt(4)
	v_mfma_f32_32x32x16_bf16 v[82:97], v[172:175], v[114:117], v[82:97]
	ds_read_b128 v[172:175], v201 offset:49280
	v_exp_f32_e32 v228, v157
	v_exp_f32_e32 v229, v152
	s_waitcnt lgkmcnt(4)
	v_mfma_f32_32x32x16_bf16 v[66:81], v[232:235], v[110:113], v[66:81]
	ds_read_b128 v[232:235], v201 offset:57472
	v_exp_f32_e32 v230, v153
	v_cvt_pk_bf16_f32 v152, v211, v212
	v_cvt_pk_bf16_f32 v153, v213, v215
	v_cvt_pk_bf16_f32 v157, v192, v193
	v_cvt_pk_bf16_f32 v211, v229, v230
	s_waitcnt lgkmcnt(4)
	v_mfma_f32_32x32x16_bf16 v[82:97], v[236:239], v[110:113], v[82:97]
	ds_read_b128 v[236:239], v202 offset:49280
	v_permlane32_swap_b32_e32 v152, v154
	v_permlane32_swap_b32_e32 v153, v155
	v_add_f32_e32 v249, v213, v150
	v_add_f32_e32 v249, v215, v249
	v_add_f32_e32 v249, v214, v249
	s_waitcnt lgkmcnt(4)
	v_mfma_f32_32x32x16_bf16 v[66:81], v[240:243], v[106:109], v[66:81]
	ds_read_b128 v[240:243], v202 offset:57472
	v_add_f32_e32 v249, v216, v249
	v_add_f32_e32 v249, v217, v249
	v_add_f32_e32 v249, v218, v249
	v_add_f32_e32 v249, v194, v249
	v_add_f32_e32 v248, v195, v249
	s_waitcnt lgkmcnt(4)
	v_mfma_f32_32x32x16_bf16 v[82:97], v[244:247], v[106:109], v[82:97]
	v_add_f32_e32 v248, v192, v248
	v_add_f32_e32 v248, v193, v248
	v_add_f32_e32 v248, v158, v248
	v_add_f32_e32 v248, v159, v248
	v_add_f32_e32 v248, v207, v248
	s_waitcnt lgkmcnt(3)
	v_mfma_f32_32x32x16_bf16 v[66:81], v[172:175], v[102:105], v[66:81]
	v_add_f32_e32 v248, v208, v248
	v_add_f32_e32 v248, v209, v248
	v_add_f32_e32 v248, v210, v248
	v_add_f32_e32 v248, v160, v248
	v_add_f32_e32 v248, v161, v248
	s_waitcnt lgkmcnt(2)
	v_mfma_f32_32x32x16_bf16 v[82:97], v[232:235], v[102:105], v[82:97]
	v_add_f32_e32 v248, v227, v248
	v_add_f32_e32 v248, v228, v248
	v_add_f32_e32 v248, v229, v248
	v_add_f32_e32 v181, v230, v248
	v_mov_b32_e32 v187, v181
	s_waitcnt lgkmcnt(1)
	v_mfma_f32_32x32x16_bf16 v[66:81], v[236:239], v[98:101], v[66:81]
	v_cvt_pk_bf16_f32 v148, v219, v220
	v_cvt_pk_bf16_f32 v149, v221, v222
	v_cvt_pk_bf16_f32 v150, v223, v225
	v_cvt_pk_bf16_f32 v158, v158, v159
	v_cvt_pk_bf16_f32 v159, v207, v208
	s_waitcnt lgkmcnt(0)
	v_mfma_f32_32x32x16_bf16 v[82:97], v[240:243], v[98:101], v[82:97]
	v_cvt_pk_bf16_f32 v208, v209, v210
	v_cvt_pk_bf16_f32 v210, v227, v228
	v_permlane32_swap_b32_e32 v181, v187
	v_permlane32_swap_b32_e32 v148, v150
	v_permlane32_swap_b32_e32 v149, v151
	v_cvt_pk_bf16_f32 v209, v160, v161
	v_permlane32_swap_b32_e32 v208, v210
	v_permlane32_swap_b32_e32 v156, v158
	v_permlane32_swap_b32_e32 v157, v159
	v_permlane32_swap_b32_e32 v209, v211
	v_lshl_add_u64 v[194:195], v[188:189], 0, v[170:171]
	v_lshl_add_u64 v[192:193], v[190:191], 0, v[170:171]
	ds_read_b64_tr_b16 v[172:173], v1 offset:0
	ds_read_b64_tr_b16 v[174:175], v1 offset:0x800
	ds_read_b64_tr_b16 v[212:213], v1 offset:0x1000
	ds_read_b64_tr_b16 v[214:215], v1 offset:0x1800
	ds_read_b64_tr_b16 v[216:217], v1 offset:0x2000
	ds_read_b64_tr_b16 v[218:219], v1 offset:0x2800
	ds_read_b64_tr_b16 v[220:221], v1 offset:0x3000
	ds_read_b64_tr_b16 v[222:223], v1 offset:0x3800
	s_nop 0
	s_waitcnt lgkmcnt(6)
; __device__ __forceinline__ void sel_mask_tile(f32x16& p0, f32x16& p1, unsigned wlo, unsigned whi, int hi) {
;     const unsigned NEGB = 0xff800000u;
;     const unsigned lo = wlo >> (4 * hi), h2 = whi >> (4 * hi);
; #pragma unroll
;     for (int r = 0; r < 16; ++r) {
;         const int c = (r & 3) + 8 * (r >> 2);
;         const unsigned m0 = (unsigned)__builtin_amdgcn_sbfe((int)lo, c, 1), m1 = (unsigned)__builtin_amdgcn_sbfe((int)h2, c, 1);
;         p0[r] = __uint_as_float((__float_as_uint(p0[r]) & m0) | (NEGB & ~m0));
;         p1[r] = __uint_as_float((__float_as_uint(p1[r]) & m1) | (NEGB & ~m1));
;     }
; }
; __device__ __forceinline__ void partialSM(f32x16& p0, f32x16& p1, float& m_reg, float& mn, float& alpha) {
;     float pmax = p0[0];
; #pragma unroll
;     for (int r = 1; r < 16; ++r) pmax = fmaxf(pmax, p0[r]);
; #pragma unroll
;     for (int r = 0; r < 16; ++r) pmax = fmaxf(pmax, p1[r]);
;     { auto rr = __builtin_amdgcn_permlane32_swap(__float_as_uint(pmax), __float_as_uint(pmax), false, false);
;       pmax = fmaxf(__uint_as_float(rr[0]), __uint_as_float(rr[1])); }
;     constexpr float C2 = 1.4426950408889634f * SCALE;
;     if (__builtin_expect(__all((pmax - m_reg) * SCALE <= THR), 1)) { mn = m_reg; alpha = 1.f; }
;     else { mn = fmaxf(m_reg, pmax); alpha = __builtin_amdgcn_exp2f((m_reg - mn) * C2); m_reg = mn; }
; template <int VB>
; __device__ __forceinline__ void pv_tile(f32x16* o, int vb0, bf16x8 pa0, bf16x8 pa1, bf16x8 pa2, bf16x8 pa3) {
;     ...
;     PV_D0(0); PV_D0(1); PV_D0(2); PV_D0(3);
	v_mfma_f32_32x32x16_bf16 v[2:17], v[148:151], v[172:175], v[2:17]
	ds_read_b64_tr_b16 v[172:173], v1 offset:0x200
	ds_read_b64_tr_b16 v[174:175], v1 offset:0xa00
	s_waitcnt lgkmcnt(6)
	v_mfma_f32_32x32x16_bf16 v[2:17], v[152:155], v[212:215], v[2:17]
	ds_read_b64_tr_b16 v[212:213], v1 offset:0x1200
	ds_read_b64_tr_b16 v[214:215], v1 offset:0x1a00
	s_waitcnt lgkmcnt(6)
	v_mfma_f32_32x32x16_bf16 v[2:17], v[156:159], v[216:219], v[2:17]
	ds_read_b64_tr_b16 v[216:217], v1 offset:0x2200
	ds_read_b64_tr_b16 v[218:219], v1 offset:0x2a00
	ds_read_b64_tr_b16 v[224:225], v1 offset:0x3200
	ds_read_b64_tr_b16 v[226:227], v1 offset:0x3a00
	s_waitcnt lgkmcnt(8)
	v_mfma_f32_32x32x16_bf16 v[2:17], v[208:211], v[220:223], v[2:17]
	s_waitcnt lgkmcnt(6)
	v_mfma_f32_32x32x16_bf16 v[50:65], v[148:151], v[172:175], v[50:65]
	ds_read_b64_tr_b16 v[172:173], v1 offset:0x400
	ds_read_b64_tr_b16 v[174:175], v1 offset:0xc00
	s_waitcnt lgkmcnt(6)
	v_mfma_f32_32x32x16_bf16 v[50:65], v[152:155], v[212:215], v[50:65]
	ds_read_b64_tr_b16 v[212:213], v1 offset:0x1400
	ds_read_b64_tr_b16 v[214:215], v1 offset:0x1c00
	s_waitcnt lgkmcnt(6)
	v_mfma_f32_32x32x16_bf16 v[50:65], v[156:159], v[216:219], v[50:65]
	ds_read_b64_tr_b16 v[216:217], v1 offset:0x2400
	ds_read_b64_tr_b16 v[218:219], v1 offset:0x2c00
	ds_read_b64_tr_b16 v[220:221], v1 offset:0x3400
	ds_read_b64_tr_b16 v[222:223], v1 offset:0x3c00
	s_waitcnt lgkmcnt(8)
	v_mfma_f32_32x32x16_bf16 v[50:65], v[208:211], v[224:227], v[50:65]
	s_waitcnt lgkmcnt(6)
	v_mfma_f32_32x32x16_bf16 v[34:49], v[148:151], v[172:175], v[34:49]
	ds_read_b64_tr_b16 v[172:173], v1 offset:0x600
	ds_read_b64_tr_b16 v[174:175], v1 offset:0xe00
	s_waitcnt lgkmcnt(6)
	v_mfma_f32_32x32x16_bf16 v[34:49], v[152:155], v[212:215], v[34:49]
	ds_read_b64_tr_b16 v[212:213], v1 offset:0x1600
	ds_read_b64_tr_b16 v[214:215], v1 offset:0x1e00
	s_waitcnt lgkmcnt(6)
	v_mfma_f32_32x32x16_bf16 v[34:49], v[156:159], v[216:219], v[34:49]
	ds_read_b64_tr_b16 v[216:217], v1 offset:0x2600
	ds_read_b64_tr_b16 v[218:219], v1 offset:0x2e00
	ds_read_b64_tr_b16 v[224:225], v1 offset:0x3600
	ds_read_b64_tr_b16 v[226:227], v1 offset:0x3e00
	s_waitcnt lgkmcnt(8)
	v_mfma_f32_32x32x16_bf16 v[34:49], v[208:211], v[220:223], v[34:49]
	s_waitcnt vmcnt(4)
	v_lshrrev_b32_e32 v160, v163, v146
	v_lshrrev_b32_e32 v161, v163, v147
	v_bfe_i32 v146, v160, 0, 1
	v_bfe_i32 v147, v161, 0, 1
	v_bitop3_b32 v146, v66, s74, v146 bitop3:0xe4
	v_bitop3_b32 v66, v82, s74, v147 bitop3:0xe4
	v_bfe_i32 v82, v160, 1, 1
	v_bfe_i32 v147, v161, 1, 1
	v_bitop3_b32 v82, v67, s74, v82 bitop3:0xe4
	v_bitop3_b32 v67, v83, s74, v147 bitop3:0xe4
	v_bfe_i32 v83, v160, 2, 1
	v_bfe_i32 v147, v161, 2, 1
	v_bitop3_b32 v83, v68, s74, v83 bitop3:0xe4
	v_bitop3_b32 v68, v84, s74, v147 bitop3:0xe4
	v_bfe_i32 v84, v160, 3, 1
	s_waitcnt lgkmcnt(6)
	v_mfma_f32_32x32x16_bf16 v[18:33], v[148:151], v[172:175], v[18:33]
	v_bfe_i32 v148, v161, 3, 1
	v_bitop3_b32 v147, v69, s74, v84 bitop3:0xe4
	v_bfe_i32 v84, v160, 8, 1
	v_bitop3_b32 v69, v85, s74, v148 bitop3:0xe4
	v_bfe_i32 v85, v161, 8, 1
	v_bitop3_b32 v148, v70, s74, v84 bitop3:0xe4
	v_bfe_i32 v84, v160, 9, 1
	v_bitop3_b32 v70, v86, s74, v85 bitop3:0xe4
	v_bfe_i32 v85, v161, 9, 1
	v_bitop3_b32 v149, v71, s74, v84 bitop3:0xe4
	v_bfe_i32 v84, v160, 10, 1
	v_bitop3_b32 v71, v87, s74, v85 bitop3:0xe4
	v_bfe_i32 v85, v161, 10, 1
	v_bitop3_b32 v87, v72, s74, v84 bitop3:0xe4
	v_bfe_i32 v84, v160, 11, 1
	v_bitop3_b32 v72, v88, s74, v85 bitop3:0xe4
	v_bfe_i32 v85, v161, 11, 1
	v_bitop3_b32 v88, v73, s74, v84 bitop3:0xe4
	v_bfe_i32 v73, v160, 16, 1
	v_bitop3_b32 v84, v89, s74, v85 bitop3:0xe4
	v_bfe_i32 v85, v161, 16, 1
	v_bitop3_b32 v89, v74, s74, v73 bitop3:0xe4
	v_bfe_i32 v73, v160, 17, 1
	v_bfe_i32 v74, v161, 17, 1
	v_bitop3_b32 v85, v90, s74, v85 bitop3:0xe4
	v_bitop3_b32 v90, v75, s74, v73 bitop3:0xe4
	v_bitop3_b32 v86, v91, s74, v74 bitop3:0xe4
	v_bfe_i32 v73, v160, 18, 1
	v_bfe_i32 v74, v161, 18, 1
	v_bitop3_b32 v91, v76, s74, v73 bitop3:0xe4
	v_bitop3_b32 v76, v92, s74, v74 bitop3:0xe4
	v_bfe_i32 v73, v160, 19, 1
	v_bfe_i32 v74, v161, 19, 1
	v_bitop3_b32 v92, v77, s74, v73 bitop3:0xe4
	v_bitop3_b32 v77, v93, s74, v74 bitop3:0xe4
	v_bfe_i32 v73, v160, 24, 1
	v_bfe_i32 v74, v161, 24, 1
	v_bitop3_b32 v93, v78, s74, v73 bitop3:0xe4
	v_bitop3_b32 v78, v94, s74, v74 bitop3:0xe4
	v_bfe_i32 v73, v160, 25, 1
	v_bfe_i32 v74, v161, 25, 1
	v_bitop3_b32 v79, v79, s74, v73 bitop3:0xe4
	v_bitop3_b32 v73, v95, s74, v74 bitop3:0xe4
	v_bfe_i32 v74, v160, 26, 1
	v_bfe_i32 v75, v161, 26, 1
	v_bitop3_b32 v80, v80, s74, v74 bitop3:0xe4
	v_bitop3_b32 v74, v96, s74, v75 bitop3:0xe4
	v_bfe_i32 v75, v160, 27, 1
	v_bfe_i32 v94, v161, 27, 1
	v_bitop3_b32 v81, v81, s74, v75 bitop3:0xe4
	v_bitop3_b32 v75, v97, s74, v94 bitop3:0xe4
	v_max_f32_e32 v94, v82, v82
	v_max_f32_e32 v95, v146, v146
	v_max_f32_e32 v94, v95, v94
	v_max3_f32 v94, v94, v83, v147
	v_max3_f32 v94, v94, v148, v149
	v_max3_f32 v94, v94, v87, v88
	v_max3_f32 v94, v94, v89, v90
	s_waitcnt lgkmcnt(4)
	v_mfma_f32_32x32x16_bf16 v[18:33], v[152:155], v[212:215], v[18:33]
	v_max3_f32 v94, v94, v91, v92
	v_max3_f32 v94, v94, v93, v79
	v_max3_f32 v94, v94, v80, v81
	v_max3_f32 v94, v94, v66, v67
	v_max3_f32 v94, v94, v68, v69
	v_max3_f32 v94, v94, v70, v71
	v_max3_f32 v94, v94, v72, v84
	v_max3_f32 v94, v94, v85, v86
	s_waitcnt lgkmcnt(2)
	v_mfma_f32_32x32x16_bf16 v[18:33], v[156:159], v[216:219], v[18:33]
	v_max3_f32 v94, v94, v76, v77
	v_max3_f32 v94, v94, v78, v73
	v_max3_f32 v94, v94, v74, v75
	v_mov_b32_e32 v95, v94
	s_nop 1
	v_permlane32_swap_b32_e32 v94, v95
	v_max_f32_e32 v95, v95, v95
	v_max_f32_e32 v94, v94, v94
	v_max_f32_e32 v94, v94, v95
	v_max_f32_e32 v96, v206, v206
	v_sub_f32_e32 v95, v94, v206
	v_max_f32_e32 v94, v96, v94
	s_waitcnt lgkmcnt(0)
	v_mfma_f32_32x32x16_bf16 v[18:33], v[208:211], v[224:227], v[18:33]
	v_sub_f32_e32 v96, v206, v94
	v_mul_f32_e32 v96, 0x3e0293ee, v96
	v_mul_f32_e32 v95, 0x3db504f3, v95
	v_exp_f32_e32 v96, v96
	v_cmp_ge_f32_e32 vcc, s75, v95
	s_cmp_eq_u64 vcc, exec
	s_cselect_b64 s[6:7], -1, 0
	s_barrier
	s_waitcnt vmcnt(0)
	v_cndmask_b32_e64 v208, v96, 1.0, s[6:7]
	v_cmp_gt_f32_e32 vcc, 1.0, v208
	ds_write_b128 v197, v[130:133]
	ds_write_b128 v198, v[134:137]
	ds_write_b128 v204, v[138:141] offset:32768
	ds_write_b128 v204, v[142:145] offset:40960
	s_cbranch_vccz .LBB0_1303
	s_and_saveexec_b64 s[36:37], s[0:1]
	ds_write_b32 v185, v208 offset:128
	s_or_b64 exec, exec, s[36:37]
	s_waitcnt lgkmcnt(0)
	ds_read_b128 v[150:153], v183 offset:224
	ds_read_b128 v[154:157], v183 offset:192
	ds_read_b128 v[158:161], v183 offset:160
	ds_read_b128 v[172:175], v183 offset:128
	s_waitcnt lgkmcnt(3)
	v_pk_mul_f32 v[16:17], v[16:17], v[152:153]
	s_waitcnt lgkmcnt(2)
	v_pk_mul_f32 v[12:13], v[12:13], v[156:157]
	s_waitcnt lgkmcnt(1)
	v_pk_mul_f32 v[8:9], v[8:9], v[160:161]
	s_waitcnt lgkmcnt(0)
	v_pk_mul_f32 v[4:5], v[4:5], v[174:175]
	v_pk_mul_f32 v[14:15], v[14:15], v[150:151]
	v_pk_mul_f32 v[10:11], v[10:11], v[154:155]
	v_pk_mul_f32 v[6:7], v[6:7], v[158:159]
	v_pk_mul_f32 v[2:3], v[2:3], v[172:173]
	v_pk_mul_f32 v[64:65], v[64:65], v[152:153]
	v_pk_mul_f32 v[60:61], v[60:61], v[156:157]
	v_pk_mul_f32 v[56:57], v[56:57], v[160:161]
	v_pk_mul_f32 v[52:53], v[52:53], v[174:175]
	v_pk_mul_f32 v[62:63], v[62:63], v[150:151]
	v_pk_mul_f32 v[58:59], v[58:59], v[154:155]
	v_pk_mul_f32 v[54:55], v[54:55], v[158:159]
	v_pk_mul_f32 v[50:51], v[50:51], v[172:173]
	v_pk_mul_f32 v[48:49], v[48:49], v[152:153]
	v_pk_mul_f32 v[44:45], v[44:45], v[156:157]
	v_pk_mul_f32 v[40:41], v[40:41], v[160:161]
	v_pk_mul_f32 v[36:37], v[36:37], v[174:175]
	v_pk_mul_f32 v[46:47], v[46:47], v[150:151]
	v_pk_mul_f32 v[42:43], v[42:43], v[154:155]
	v_pk_mul_f32 v[38:39], v[38:39], v[158:159]
	v_pk_mul_f32 v[34:35], v[34:35], v[172:173]
	v_pk_mul_f32 v[32:33], v[32:33], v[152:153]
	v_pk_mul_f32 v[28:29], v[28:29], v[156:157]
	v_pk_mul_f32 v[24:25], v[24:25], v[160:161]
	v_pk_mul_f32 v[20:21], v[20:21], v[174:175]
	v_pk_mul_f32 v[30:31], v[30:31], v[150:151]
	v_pk_mul_f32 v[26:27], v[26:27], v[154:155]
	v_pk_mul_f32 v[22:23], v[22:23], v[158:159]
	v_pk_mul_f32 v[18:19], v[18:19], v[172:173]

; __device__ __forceinline__ void sel_mask_tile(f32x16& p0, f32x16& p1, unsigned wlo, unsigned whi, int hi) {
;     const unsigned NEGB = 0xff800000u;
;     const unsigned lo = wlo >> (4 * hi), h2 = whi >> (4 * hi);
; #pragma unroll
;     for (int r = 0; r < 16; ++r) {
;         const int c = (r & 3) + 8 * (r >> 2);
;         const unsigned m0 = (unsigned)__builtin_amdgcn_sbfe((int)lo, c, 1), m1 = (unsigned)__builtin_amdgcn_sbfe((int)h2, c, 1);
;         p0[r] = __uint_as_float((__float_as_uint(p0[r]) & m0) | (NEGB & ~m0));
;         p1[r] = __uint_as_float((__float_as_uint(p1[r]) & m1) | (NEGB & ~m1));
;     }
; }
; __device__ __forceinline__ void partialSM(f32x16& p0, f32x16& p1, float& m_reg, float& mn, float& alpha) {
;     float pmax = p0[0];
; #pragma unroll
;     for (int r = 1; r < 16; ++r) pmax = fmaxf(pmax, p0[r]);
; #pragma unroll
;     for (int r = 0; r < 16; ++r) pmax = fmaxf(pmax, p1[r]);
;     { auto rr = __builtin_amdgcn_permlane32_swap(__float_as_uint(pmax), __float_as_uint(pmax), false, false);
;       pmax = fmaxf(__uint_as_float(rr[0]), __uint_as_float(rr[1])); }
;     constexpr float C2 = 1.4426950408889634f * SCALE;
;     if (__builtin_expect(__all((pmax - m_reg) * SCALE <= THR), 1)) { mn = m_reg; alpha = 1.f; }
;     else { mn = fmaxf(m_reg, pmax); alpha = __builtin_amdgcn_exp2f((m_reg - mn) * C2); m_reg = mn; }
; template <int VB>
; __device__ __forceinline__ void pv_tile(f32x16* o, int vb0, bf16x8 pa0, bf16x8 pa1, bf16x8 pa2, bf16x8 pa3) {
;     ...
;     PV_D0(0); PV_D0(1); PV_D0(2); PV_D0(3);
.LBB0_1305:
	ds_read_b64_tr_b16 v[172:173], v1 offset:0x4000
	ds_read_b64_tr_b16 v[174:175], v1 offset:0x4800
	ds_read_b64_tr_b16 v[192:193], v1 offset:0x5000
	ds_read_b64_tr_b16 v[194:195], v1 offset:0x5800
	ds_read_b64_tr_b16 v[212:213], v1 offset:0x6000
	ds_read_b64_tr_b16 v[214:215], v1 offset:0x6800
	ds_read_b64_tr_b16 v[216:217], v1 offset:0x7000
	ds_read_b64_tr_b16 v[218:219], v1 offset:0x7800
	s_nop 0
	s_waitcnt lgkmcnt(6)
	v_mfma_f32_32x32x16_bf16 v[2:17], v[146:149], v[172:175], v[2:17]
	ds_read_b64_tr_b16 v[172:173], v1 offset:0x4200
	ds_read_b64_tr_b16 v[174:175], v1 offset:0x4a00
	s_waitcnt lgkmcnt(6)
	v_mfma_f32_32x32x16_bf16 v[2:17], v[150:153], v[192:195], v[2:17]
	ds_read_b64_tr_b16 v[192:193], v1 offset:0x5200
	ds_read_b64_tr_b16 v[194:195], v1 offset:0x5a00
	s_waitcnt lgkmcnt(6)
	v_mfma_f32_32x32x16_bf16 v[2:17], v[154:157], v[212:215], v[2:17]
	ds_read_b64_tr_b16 v[212:213], v1 offset:0x6200
	ds_read_b64_tr_b16 v[214:215], v1 offset:0x6a00
	ds_read_b64_tr_b16 v[220:221], v1 offset:0x7200
	ds_read_b64_tr_b16 v[222:223], v1 offset:0x7a00
	s_waitcnt lgkmcnt(8)
	v_mfma_f32_32x32x16_bf16 v[2:17], v[158:161], v[216:219], v[2:17]
	s_waitcnt lgkmcnt(6)
	v_mfma_f32_32x32x16_bf16 v[50:65], v[146:149], v[172:175], v[50:65]
	ds_read_b64_tr_b16 v[172:173], v1 offset:0x4400
	ds_read_b64_tr_b16 v[174:175], v1 offset:0x4c00
	s_waitcnt lgkmcnt(6)
	v_mfma_f32_32x32x16_bf16 v[50:65], v[150:153], v[192:195], v[50:65]
	ds_read_b64_tr_b16 v[192:193], v1 offset:0x5400
	ds_read_b64_tr_b16 v[194:195], v1 offset:0x5c00
	s_waitcnt lgkmcnt(6)
	v_mfma_f32_32x32x16_bf16 v[50:65], v[154:157], v[212:215], v[50:65]
	ds_read_b64_tr_b16 v[212:213], v1 offset:0x6400
	ds_read_b64_tr_b16 v[214:215], v1 offset:0x6c00
	ds_read_b64_tr_b16 v[216:217], v1 offset:0x7400
	ds_read_b64_tr_b16 v[218:219], v1 offset:0x7c00
	s_waitcnt lgkmcnt(8)
	v_mfma_f32_32x32x16_bf16 v[50:65], v[158:161], v[220:223], v[50:65]
	s_waitcnt lgkmcnt(6)
	v_mfma_f32_32x32x16_bf16 v[34:49], v[146:149], v[172:175], v[34:49]
	ds_read_b64_tr_b16 v[172:173], v1 offset:0x4600
	ds_read_b64_tr_b16 v[174:175], v1 offset:0x4e00
	s_waitcnt lgkmcnt(6)
	v_mfma_f32_32x32x16_bf16 v[34:49], v[150:153], v[192:195], v[34:49]
	s_waitcnt lgkmcnt(4)
	v_mfma_f32_32x32x16_bf16 v[34:49], v[154:157], v[212:215], v[34:49]
	ds_read_b64_tr_b16 v[212:213], v1 offset:0x5600
	ds_read_b64_tr_b16 v[214:215], v1 offset:0x5e00
	ds_read_b64_tr_b16 v[220:221], v1 offset:0x6600
	ds_read_b64_tr_b16 v[222:223], v1 offset:0x6e00
	ds_read_b64_tr_b16 v[224:225], v1 offset:0x7600
	ds_read_b64_tr_b16 v[226:227], v1 offset:0x7e00
	s_waitcnt lgkmcnt(8)
	v_mfma_f32_32x32x16_bf16 v[34:49], v[158:161], v[216:219], v[34:49]
	s_waitcnt lgkmcnt(6)
	v_mfma_f32_32x32x16_bf16 v[18:33], v[146:149], v[172:175], v[18:33]
	s_waitcnt vmcnt(4)
	v_lshrrev_b32_e32 v193, v163, v228
	v_bfe_i32 v192, v193, 0, 1
	v_bitop3_b32 v192, v82, s74, v192 bitop3:0xe4
	v_bfe_i32 v82, v193, 1, 1
	v_bitop3_b32 v146, v83, s74, v82 bitop3:0xe4
	v_bfe_i32 v82, v193, 2, 1
	v_bitop3_b32 v147, v84, s74, v82 bitop3:0xe4
	s_waitcnt lgkmcnt(4)
	v_mfma_f32_32x32x16_bf16 v[18:33], v[150:153], v[212:215], v[18:33]
	v_bfe_i32 v82, v193, 3, 1
	v_bitop3_b32 v148, v85, s74, v82 bitop3:0xe4
	v_bfe_i32 v82, v193, 8, 1
	v_bitop3_b32 v149, v86, s74, v82 bitop3:0xe4
	v_bfe_i32 v82, v193, 9, 1
	v_bitop3_b32 v150, v87, s74, v82 bitop3:0xe4
	v_bfe_i32 v82, v193, 10, 1
	v_bitop3_b32 v88, v88, s74, v82 bitop3:0xe4
	v_bfe_i32 v82, v193, 11, 1
	s_waitcnt lgkmcnt(2)
	v_mfma_f32_32x32x16_bf16 v[18:33], v[154:157], v[220:223], v[18:33]
	v_bitop3_b32 v89, v89, s74, v82 bitop3:0xe4
	v_bfe_i32 v82, v193, 16, 1
	v_bitop3_b32 v90, v90, s74, v82 bitop3:0xe4
	v_bfe_i32 v82, v193, 17, 1
	v_bitop3_b32 v91, v91, s74, v82 bitop3:0xe4
	v_bfe_i32 v82, v193, 18, 1
	v_bitop3_b32 v92, v92, s74, v82 bitop3:0xe4
	v_bfe_i32 v82, v193, 19, 1
	v_bitop3_b32 v93, v93, s74, v82 bitop3:0xe4
	v_bfe_i32 v82, v193, 24, 1
	v_bitop3_b32 v94, v94, s74, v82 bitop3:0xe4
	v_bfe_i32 v82, v193, 25, 1
	v_bitop3_b32 v95, v95, s74, v82 bitop3:0xe4
	v_bfe_i32 v82, v193, 26, 1
	v_bitop3_b32 v96, v96, s74, v82 bitop3:0xe4
	v_bfe_i32 v82, v193, 27, 1
	s_waitcnt lgkmcnt(0)
	v_mfma_f32_32x32x16_bf16 v[18:33], v[158:161], v[224:227], v[18:33]
	v_bitop3_b32 v97, v97, s74, v82 bitop3:0xe4
	v_max_f32_e32 v82, v146, v146
	v_max_f32_e32 v160, v192, v192
	v_max_f32_e32 v82, v160, v82
	v_max3_f32 v82, v82, v147, v148
	v_max3_f32 v82, v82, v149, v150
	v_max3_f32 v82, v82, v88, v89
	v_max3_f32 v82, v82, v90, v91
	v_lshrrev_b32_e32 v194, v163, v229
	v_max3_f32 v82, v82, v92, v93
	v_bfe_i32 v195, v194, 0, 1
	v_bfe_i32 v172, v194, 1, 1
	v_max3_f32 v82, v82, v94, v95
	v_bitop3_b32 v66, v66, s74, v195 bitop3:0xe4
	v_bfe_i32 v83, v194, 2, 1
	v_bfe_i32 v84, v194, 3, 1
	v_max3_f32 v160, v82, v96, v97
	v_bitop3_b32 v67, v67, s74, v172 bitop3:0xe4
	v_bfe_i32 v85, v194, 8, 1
	v_bfe_i32 v86, v194, 9, 1
	v_bitop3_b32 v82, v68, s74, v83 bitop3:0xe4
	v_max3_f32 v68, v160, v66, v67
	v_bitop3_b32 v83, v69, s74, v84 bitop3:0xe4
	v_bfe_i32 v87, v194, 10, 1
	v_bfe_i32 v151, v194, 11, 1
	v_bitop3_b32 v84, v70, s74, v85 bitop3:0xe4
	v_max3_f32 v68, v68, v82, v83
	v_bitop3_b32 v85, v71, s74, v86 bitop3:0xe4
	v_bfe_i32 v152, v194, 16, 1
	v_bfe_i32 v153, v194, 17, 1
	v_bitop3_b32 v86, v72, s74, v87 bitop3:0xe4
	v_max3_f32 v68, v68, v84, v85
	v_bitop3_b32 v87, v73, s74, v151 bitop3:0xe4
	v_bfe_i32 v154, v194, 18, 1
	v_bfe_i32 v155, v194, 19, 1
	v_bitop3_b32 v74, v74, s74, v152 bitop3:0xe4
	v_max3_f32 v69, v68, v86, v87
	v_bitop3_b32 v75, v75, s74, v153 bitop3:0xe4
	v_bfe_i32 v156, v194, 24, 1
	v_bfe_i32 v157, v194, 25, 1
	v_bitop3_b32 v68, v76, s74, v154 bitop3:0xe4
	v_max3_f32 v71, v69, v74, v75
	v_bitop3_b32 v69, v77, s74, v155 bitop3:0xe4
	v_bfe_i32 v158, v194, 26, 1
	v_bfe_i32 v159, v194, 27, 1
	v_bitop3_b32 v70, v78, s74, v156 bitop3:0xe4
	v_max3_f32 v73, v71, v68, v69
	v_bitop3_b32 v71, v79, s74, v157 bitop3:0xe4
	v_bitop3_b32 v72, v80, s74, v158 bitop3:0xe4
	v_max3_f32 v76, v73, v70, v71
	v_bitop3_b32 v73, v81, s74, v159 bitop3:0xe4
	v_max3_f32 v76, v76, v72, v73
	v_mov_b32_e32 v77, v76
	s_nop 1
	v_permlane32_swap_b32_e32 v76, v77
	v_max_f32_e32 v77, v77, v77
	v_max_f32_e32 v76, v76, v76
	v_max_f32_e32 v76, v76, v77
	v_sub_f32_e32 v77, v76, v206
	v_mul_f32_e32 v77, 0x3db504f3, v77
	v_cmp_ge_f32_e32 vcc, s75, v77
	s_cmp_eq_u64 vcc, exec
	s_cselect_b64 s[6:7], -1, 0
	s_andn2_b64 vcc, exec, s[36:37]
	s_barrier
	s_cbranch_vccnz .LBB0_1307
	s_waitcnt vmcnt(0)
	ds_write_b128 v197, v[130:133] offset:16384
	ds_write_b128 v198, v[134:137] offset:16384
	ds_write_b128 v204, v[138:141] offset:49152
	ds_write_b128 v204, v[142:145] offset:57344
